# speedup vs baseline: 1.0150x; 1.0046x over previous
; #define SBAR() __builtin_amdgcn_sched_barrier(0)
; #define ARESC(o, a) do { if (__any((a) < 1.f)) { if (hi == 0) al_l[r32] = (a); asm volatile("s_waitcnt lgkmcnt(0)" ::: "memory"); \
;     _Pragma("unroll") for (int d = 0; d < 4; ++d) _Pragma("unroll") for (int r = 0; r < 16; ++r) o[d][r] *= al_l[crow(r, hi)]; } } while (0)
; __device__ __forceinline__ void qkt2(f32x16& p0, f32x16& p1, const char* Ks, const bf16x8* qr, int r32, int hi, int cbase) {
; #pragma unroll
;   for (int r = 0; r < 16; ++r) { p0[r] = 0.f; p1[r] = 0.f; }
; #pragma unroll
;   for (int d0 = 0; d0 < 4; ++d0) { const int cb = cbase + (d0 * 16 + hi * 8) * 2;
;     const bf16x8 b0 = *reinterpret_cast<const bf16x8*>(Ks + KSWZ(r32, cb));
;     const bf16x8 b1 = *reinterpret_cast<const bf16x8*>(Ks + KSWZ(32 + r32, cb));
;     p0 = __builtin_amdgcn_mfma_f32_32x32x16_bf16(b0, qr[d0], p0, 0, 0, 0);
;     p1 = __builtin_amdgcn_mfma_f32_32x32x16_bf16(b1, qr[d0], p1, 0, 0, 0); }
; }
; __device__ __forceinline__ void attn_fused(const Params& p, int layer, float lam, float lam_init, int q0, int tok0, int h, int seq, char* lds) {
;     ...
;   for (int j = 0; j < NT; ++j) {
;     const int b = j & 1;
;     if (j + 1 < NT) ADMA(b ^ 1, (j + 1) * 64);
;     const char* Kb = lds + AF_K + b * 16384; const int vb = vb0 + b * 16384;
;     f32x16 p0, p1; float mn, alpha; bf16x8 pa0, pa1, pa2, pa3;
;     qkt2(p0, p1, Kb, qr, r32, hi, 0); partialSM(p0, p1, m0, mn, alpha); ARESC(oa, alpha);
;     finishSM(p0, p1, alpha, l0, pa0, pa1, pa2, pa3); SBAR(); pv_d0(oa, vb, pa0, pa1, pa2, pa3);
.LBB0_121:
	s_add_i32 s2, s60, -1
	s_and_b32 s62, s2, 1
	s_lshl_b32 s2, s62, 14
	v_add3_u32 v128, s2, v227, v206
	ds_read_b128 v[128:131], v128
	v_add3_u32 v132, s2, v227, v206
	ds_read_b128 v[132:135], v132 offset:8192
	v_add3_u32 v244, s2, v228, v206
	ds_read_b128 v[244:247], v244
	v_add3_u32 v248, s2, v228, v206
	ds_read_b128 v[248:251], v248 offset:8192
	v_add3_u32 v208, s2, v229, v206
	ds_read_b128 v[208:211], v208
	v_add3_u32 v216, s2, v229, v206
	ds_read_b128 v[216:219], v216 offset:8192
	v_add3_u32 v222, s2, v230, v206
	ds_read_b128 v[222:225], v222
	v_add_u32_e32 v242, s2, v206
	s_cmp_lt_u32 s60, s33
	s_cbranch_scc0 .Lmy_att_nodma
	s_xor_b32 s12, s2, 0x4000
	s_add_i32 s12, s35, s12
	v_lshl_add_u64 v[136:137], v[196:197], 0, s[48:49]
	s_mov_b32 m0, s12
	s_nop 0
	global_load_lds_dwordx4 v[136:137], off
	v_lshl_add_u64 v[136:137], v[198:199], 0, s[48:49]
	s_add_i32 m0, s12, 0x8000
	s_nop 0
	global_load_lds_dwordx4 v[136:137], off
	v_lshl_add_u64 v[136:137], v[194:195], 0, s[48:49]
	s_add_i32 m0, s12, 0x2000
	s_nop 0
	global_load_lds_dwordx4 v[136:137], off
	v_lshl_add_u64 v[136:137], v[200:201], 0, s[48:49]
	s_add_i32 m0, s12, 0xa000
	s_nop 0
	global_load_lds_dwordx4 v[136:137], off
.Lmy_att_nodma:
	s_waitcnt lgkmcnt(6)
	v_mfma_f32_32x32x16_bf16 v[144:159], v[128:131], v[160:163], 0
	s_waitcnt lgkmcnt(5)
	v_mfma_f32_32x32x16_bf16 v[128:143], v[132:135], v[160:163], 0
	s_waitcnt lgkmcnt(4)
	v_mfma_f32_32x32x16_bf16 v[144:159], v[244:247], v[164:167], v[144:159]
	v_add3_u32 v244, s2, v230, v206
	ds_read_b128 v[244:247], v244 offset:8192
	s_waitcnt lgkmcnt(4)
	v_mfma_f32_32x32x16_bf16 v[128:143], v[248:251], v[164:167], v[128:143]
	s_waitcnt lgkmcnt(3)
	v_mfma_f32_32x32x16_bf16 v[144:159], v[208:211], v[168:171], v[144:159]
	s_waitcnt lgkmcnt(2)
	v_mfma_f32_32x32x16_bf16 v[128:143], v[216:219], v[168:171], v[128:143]
	s_waitcnt lgkmcnt(1)
	v_mfma_f32_32x32x16_bf16 v[144:159], v[222:225], v[172:175], v[144:159]
	s_waitcnt lgkmcnt(0)
	v_mfma_f32_32x32x16_bf16 v[128:143], v[244:247], v[172:175], v[128:143]
	s_nop 10
	v_max3_f32 v208, v144, v145, v146
	v_max3_f32 v209, v152, v153, v154
	v_max3_f32 v208, v208, v147, v148
	v_max3_f32 v209, v209, v155, v156
	v_max3_f32 v208, v208, v149, v150
	v_max3_f32 v209, v209, v157, v158
	v_max3_f32 v208, v208, v151, v159
	v_max3_f32 v210, v128, v129, v130
	v_max3_f32 v211, v136, v137, v138
	v_max3_f32 v210, v210, v131, v132
	v_max3_f32 v211, v211, v139, v140
	v_max3_f32 v210, v210, v133, v134
	v_max3_f32 v211, v211, v141, v142
	v_max3_f32 v210, v210, v135, v143
	v_max3_f32 v208, v208, v209, v210
	v_max_f32_e32 v208, v208, v211
	v_mov_b32_e32 v209, v208
	s_nop 1
	v_permlane32_swap_b32_e32 v208, v209
	v_max_f32_e32 v236, v208, v209
	v_sub_f32_e32 v208, v236, v243
	v_cmp_ge_f32_e32 vcc, s0, v208
	s_cmp_lg_u64 vcc, exec
	s_cbranch_scc1 .LBB0_141
	v_mov_b32_e32 v239, v243
	v_mov_b32_e32 v240, 1.0
	v_mov_b32_e32 v236, v243
	s_branch .LBB0_132
